# asymmetric conversion windows: layer-1 IN and F1O weights (2304 items) converted by the idle CUs in layer 0's mix-in round instead of up front; on top of k-snake + scalar-base DMA addressing
# speedup vs baseline: 1.0057x; 1.0057x over previous
.LBB0_10:
	s_movk_i32 s0, 0x1400
	v_writelane_b32 v247, s0, 0
	s_movk_i32 s0, 0x1000
	s_nop 0
	v_writelane_b32 v247, s0, 8
	s_movk_i32 s0, 0x7fff
	s_nop 0
	v_writelane_b32 v247, s0, 9
	s_mov_b32 s0, 0
	s_nop 1
	v_writelane_b32 v247, s0, 1
	s_nop 1
	v_writelane_b32 v247, s0, 3
	s_nop 1
	v_writelane_b32 v247, s0, 6
	s_movk_i32 s0, 0xb00
	s_nop 0
	v_writelane_b32 v247, s0, 2
	s_movk_i32 s0, 0x1f00
	s_nop 0
	v_writelane_b32 v247, s0, 5
	s_waitcnt lgkmcnt(0)
	s_lshl_b32 s0, s66, 3
	s_nop 0
	v_writelane_b32 v247, s0, 4
	s_lshr_b32 s100, s2, 6
	s_lshl_b32 s0, s74, 3
	s_add_i32 s100, s100, s0

.Lwin_all:
	v_writelane_b32 v242, s0, 0
	s_nop 1
	v_writelane_b32 v242, s1, 1
	s_nop 1
	v_writelane_b32 v242, s2, 2
	s_nop 1
	v_writelane_b32 v242, s3, 3
	s_nop 1
	v_writelane_b32 v242, s4, 4
	s_nop 1
	v_writelane_b32 v242, s5, 5
	s_nop 1
	v_writelane_b32 v242, s6, 6
	s_nop 1
	v_writelane_b32 v242, s7, 7
	s_nop 1
	v_writelane_b32 v242, s8, 8
	s_nop 1
	v_writelane_b32 v242, s9, 9
	s_nop 1
	v_writelane_b32 v242, s10, 10
	s_nop 1
	v_writelane_b32 v242, s11, 11
	s_nop 1
	v_writelane_b32 v242, s12, 12
	s_nop 1
	v_writelane_b32 v242, s13, 13
	s_nop 1
	v_writelane_b32 v242, s14, 14
	s_nop 1
	v_writelane_b32 v242, s15, 15
	s_nop 1
	v_writelane_b32 v242, s16, 16
	s_nop 1
	v_writelane_b32 v242, s17, 17
	s_nop 1
	v_writelane_b32 v242, s18, 18
	s_nop 1
	v_writelane_b32 v242, s19, 19
	s_nop 1
	v_writelane_b32 v242, s20, 20
	s_nop 1
	v_writelane_b32 v242, s21, 21
	s_nop 1
	v_writelane_b32 v242, s22, 22
	s_nop 1
	v_writelane_b32 v242, s23, 23
	s_nop 1
	v_writelane_b32 v242, s24, 24
	s_nop 1
	v_writelane_b32 v242, s25, 25
	s_nop 1
	v_writelane_b32 v242, s26, 26
	s_nop 1
	v_writelane_b32 v242, s27, 27
	s_nop 1
	v_writelane_b32 v242, s28, 28
	s_nop 1
	v_writelane_b32 v242, s29, 29
	s_nop 1
	v_writelane_b32 v242, s30, 30
	s_nop 1
	v_writelane_b32 v242, s31, 31
	s_nop 1
	v_writelane_b32 v242, s32, 32
	s_nop 1
	v_writelane_b32 v242, s33, 33
	s_nop 1
	v_writelane_b32 v242, s34, 34
	s_nop 1
	v_writelane_b32 v242, s35, 35
	s_nop 1
	v_writelane_b32 v242, s36, 36
	s_nop 1
	v_writelane_b32 v242, s37, 37
	s_nop 1
	v_writelane_b32 v242, s38, 38
	s_nop 1
	v_writelane_b32 v242, s39, 39
	s_nop 1
	v_writelane_b32 v242, s40, 40
	s_nop 1
	v_writelane_b32 v242, s41, 41
	s_nop 1
	v_writelane_b32 v242, s42, 42
	s_nop 1
	v_writelane_b32 v242, s43, 43
	s_nop 1
	v_writelane_b32 v242, s44, 44
	s_nop 1
	v_writelane_b32 v242, s45, 45
	s_nop 1
	v_writelane_b32 v242, s46, 46
	s_nop 1
	v_writelane_b32 v242, s47, 47
	s_nop 1
	v_writelane_b32 v242, s48, 48
	s_nop 1
	v_writelane_b32 v242, s49, 49
	s_nop 1
	v_writelane_b32 v242, s50, 50
	s_nop 1
	v_writelane_b32 v242, s51, 51
	s_nop 1
	v_writelane_b32 v242, s52, 52
	s_nop 1
	v_writelane_b32 v242, s53, 53
	s_nop 1
	v_writelane_b32 v242, s54, 54
	s_nop 1
	v_writelane_b32 v242, s55, 55
	s_nop 1
	v_writelane_b32 v242, s56, 56
	s_nop 1
	v_writelane_b32 v242, s57, 57
	s_nop 1
	v_writelane_b32 v242, s58, 58
	s_nop 1
	v_writelane_b32 v242, s59, 59
	s_nop 1
	v_writelane_b32 v242, s60, 60
	s_nop 1
	v_writelane_b32 v242, s61, 61
	s_nop 1
	v_writelane_b32 v242, s62, 62
	s_nop 1
	v_writelane_b32 v242, s63, 63
	s_nop 1
	v_writelane_b32 v243, s64, 0
	s_nop 1
	v_writelane_b32 v243, s65, 1
	s_nop 1
	v_writelane_b32 v243, s66, 2
	s_nop 1
	v_writelane_b32 v243, s67, 3
	s_nop 1
	v_writelane_b32 v243, s68, 4
	s_nop 1
	v_writelane_b32 v243, s69, 5
	s_nop 1
	v_writelane_b32 v243, s70, 6
	s_nop 1
	v_writelane_b32 v243, s71, 7
	s_nop 1
	v_writelane_b32 v243, s72, 8
	s_nop 1
	v_writelane_b32 v243, s73, 9
	s_nop 1
	v_writelane_b32 v243, s74, 10
	s_nop 1
	v_writelane_b32 v243, s75, 11
	s_nop 1
	v_writelane_b32 v243, s76, 12
	s_nop 1
	v_writelane_b32 v243, s77, 13
	s_nop 1
	v_writelane_b32 v243, s78, 14
	s_nop 1
	v_writelane_b32 v243, s79, 15
	s_nop 1
	v_writelane_b32 v243, s80, 16
	s_nop 1
	v_writelane_b32 v243, s81, 17
	s_nop 1
	v_writelane_b32 v243, s82, 18
	s_nop 1
	v_writelane_b32 v243, s83, 19
	s_nop 1
	v_writelane_b32 v243, s84, 20
	s_nop 1
	v_writelane_b32 v243, s85, 21
	s_nop 1
	v_writelane_b32 v243, s86, 22
	s_nop 1
	v_writelane_b32 v243, s87, 23
	s_nop 1
	v_writelane_b32 v243, s88, 24
	s_nop 1
	v_writelane_b32 v243, s89, 25
	s_nop 1
	v_writelane_b32 v243, s90, 26
	s_nop 1
	v_writelane_b32 v243, s91, 27
	s_nop 1
	v_writelane_b32 v243, s92, 28
	s_nop 1
	v_writelane_b32 v243, s93, 29
	s_nop 1
	v_writelane_b32 v243, s94, 30
	s_nop 1
	v_writelane_b32 v243, s95, 31
	s_nop 1
	v_writelane_b32 v243, s96, 32
	s_nop 1
	v_writelane_b32 v243, s97, 33
	s_nop 1
	v_writelane_b32 v243, s98, 34
	s_nop 1
	v_writelane_b32 v243, s99, 35
	s_nop 1
	v_writelane_b32 v243, vcc_lo, 36
	s_nop 1
	v_writelane_b32 v243, vcc_hi, 37
	s_mov_b64 s[0:1], exec
	s_nop 1
	v_writelane_b32 v243, s0, 38
	s_nop 1
	v_writelane_b32 v243, s1, 39
	s_mov_b64 exec, -1
	v_mov_b32_e32 v244, v241
	v_mov_b32_e32 v245, v4
	v_mov_b32_e32 v246, v33
	s_cmp_gt_u32 s70, 2
	s_cselect_b32 s4, 1, 0
	s_nop 0
	v_writelane_b32 v247, s4, 3
	s_movk_i32 s5, 0x1b80
	s_cmp_gt_u32 s70, 2
	s_cselect_b32 s4, 0x1280, s5
	s_nop 0
	v_writelane_b32 v247, s4, 0
	s_nop 1
	v_writelane_b32 v247, s4, 5
	s_movk_i32 s5, 0x1280
	s_cmp_gt_u32 s70, 2
	s_cselect_b32 s4, 0x7fff, s5
	s_nop 0
	v_writelane_b32 v247, s4, 9
	s_movk_i32 s5, 0x2a00
	s_cmp_gt_u32 s70, 2
	s_cselect_b32 s4, 0x7fff, s5
	s_nop 0
	v_writelane_b32 v247, s4, 8
	s_movk_i32 s4, 0xb00
	s_nop 0
	v_writelane_b32 v247, s4, 1
	s_movk_i32 s4, 0x1400
	s_nop 0
	v_writelane_b32 v247, s4, 2
	s_lshl_b32 s4, s66, 3
	s_cmpk_eq_i32 s66, 0x100
	s_cselect_b32 s4, 0x400, s4
	s_cselect_b32 s3, 0x400, 0
	s_nop 0
	v_writelane_b32 v247, s4, 4
	s_mov_b32 s4, 1
	s_nop 0
	v_writelane_b32 v247, s4, 6
	s_load_dwordx8 s[8:15], s[30:31], 0x0
	s_load_dwordx4 s[24:27], s[30:31], 0x20
	s_load_dwordx2 s[6:7], s[30:31], 0x30
	s_load_dwordx4 s[64:67], s[30:31], 0xb0
	v_readfirstlane_b32 s2, v156
	s_lshl_b32 s4, s74, 3
	s_lshr_b32 s100, s2, 6
	s_add_i32 s100, s100, s4
	s_sub_i32 s100, s100, s3
	s_waitcnt lgkmcnt(0)
	s_branch .Lconv_pre
